# phase W: the per-layer lambda scalar (256 serial loads by one thread) computed by the last thread of the grid, whose wave has one fewer weight-transpose item, instead of thread 0 (critical path)
# speedup vs baseline: 1.0230x; 1.0035x over previous
; __device__ __forceinline__ void phase_W(CArgs& a, int l, LAS unsigned char* lds, const int tid, const int bx, const int G) {
;     ...
;     const int gt = bx * NTHR + tid, NGT = G * NTHR;
;     if (l == 0) {
;     ...
;     if (gt == 0) {
;         const float* lp = a.in[I_LAM] + l * 256; float s1 = 0.f, s2 = 0.f;
;         for (int i = 0; i < 64; ++i) { s1 += lp[i] * lp[64 + i]; s2 += lp[128 + i] * lp[192 + i]; }
;         ((float*)(ws + WS_LAM))[l] = expf(s1) - expf(s2) + (0.8f - 0.6f * expf(-0.3f * (float)l));
;     }
.LBB0_508:
	s_or_b64 exec, exec, s[12:13]
	s_andn2_b64 vcc, exec, s[4:5]
	v_lshl_add_u32 v2, s9, 9, v61
	s_cbranch_vccz .LBB0_513
	s_lshl_b32 s95, s37, 9
	s_add_i32 s95, s95, -1
	v_cmp_eq_u32_e32 vcc, s95, v2
	s_and_saveexec_b64 s[12:13], vcc
	s_cbranch_execnz .LBB0_521
	s_branch .LBB0_524

; __device__ __forceinline__ void phase_W(CArgs& a, int l, LAS unsigned char* lds, const int tid, const int bx, const int G) {
;     ...
;     if (gt == 0) {
;         const float* lp = a.in[I_LAM] + l * 256; float s1 = 0.f, s2 = 0.f;
;         for (int i = 0; i < 64; ++i) { s1 += lp[i] * lp[64 + i]; s2 += lp[128 + i] * lp[192 + i]; }
;         ((float*)(ws + WS_LAM))[l] = expf(s1) - expf(s2) + (0.8f - 0.6f * expf(-0.3f * (float)l));
;     }
.LBB0_520:
	s_or_b64 exec, exec, s[12:13]
	s_lshl_b32 s95, s37, 9
	s_add_i32 s95, s95, -1
	v_cmp_eq_u32_e32 vcc, s95, v2
	s_and_saveexec_b64 s[12:13], vcc
	s_cbranch_execz .LBB0_524
